# in-proj v tiles: extra lane-xor-2 butterfly so each lane stores 4 consecutive tokens: 2 dwordx2 stores per group instead of 4 dword stores (bit-identical); includes DPP/v_perm pair exchange; on top of
# speedup vs baseline: 1.0088x; 1.0088x over previous
; __device__ __forceinline__ unsigned cvt_pk_bf16(float lo, float hi) { unsigned r; asm volatile("v_cvt_pk_bf16_f32 %0, %1, %2" : "=v"(r) : "v"(lo), "v"(hi)); return r; }
;     __device__ __forceinline__ void operator()(const f32x4 (&acc)[2][2][4][2], const Unit& u, int wr, int wc, int fr, int fq) const {
;     ...
;         } else if (u.pn >= 12) {
;             const int odd = fr & 1;
; #pragma unroll
;             for (int ai = 0; ai < 2; ++ai)
; #pragma unroll
;                 for (int m = 0; m < 4; ++m) { const int tokrow = row0 + ai * HALF + m * 16;
; #pragma unroll
;                     for (int bj = 0; bj < 2; ++bj) {
;                         const f32x4 v0 = acc[ai][bj][m][0], v1 = acc[ai][bj][m][1];
;                         u32x4 w; w.x = cvt_pk_bf16(v0[0], v0[1]); w.y = cvt_pk_bf16(v0[2], v0[3]); w.z = cvt_pk_bf16(v1[0], v1[1]); w.w = cvt_pk_bf16(v1[2], v1[3]);
;                         bf16_t* vt = KT + (size_t)(512 + (u.pn - 12) * BM + bj * HALF + wc * 32 + 8 * fq + odd) * ldk + (tokrow - odd);
; #pragma unroll
;                         for (int q = 0; q < 4; ++q) { const unsigned mine = w[q], other = (unsigned)__shfl_xor((int)mine, 1);
;                             const unsigned pr = odd ? ((other >> 16) | (mine & 0xffff0000u)) : ((mine & 0xffffu) | (other << 16));
;                             *(unsigned*)(vt + (size_t)(2 * q) * ldk) = pr; }
;                     } }
.LBB0_274:
	s_andn2_b64 vcc, exec, s[16:17]
	s_cbranch_vccnz .LBB0_532
	s_mov_b32 s98, 0xcccccccc
	s_mov_b32 s99, 0xcccccccc
	v_and_b32_e32 v148, 2, v160
	v_mul_u32_u24_e32 v148, 0x1107e, v148
	v_mov_b32_e32 v149, 0
	v_mov_b32_e32 v150, 0x44200
	v_mov_b32_e32 v151, 0
	v_cmp_lt_i32_e32 vcc, v228, v222
	v_cvt_pk_bf16_f32 v128, v124, v125
	v_cvt_pk_bf16_f32 v135, v126, v127
	v_cvt_pk_bf16_f32 v133, v120, v121
	v_cvt_pk_bf16_f32 v132, v122, v123
	s_nop 1
	v_cndmask_b32_e32 v129, v221, v228, vcc
	v_lshlrev_b32_e32 v134, 2, v129
	s_nop 1
	v_mov_b32_dpp v129, v128 quad_perm:[1,0,3,2] row_mask:0xf bank_mask:0xf
	v_perm_b32 v140, v129, v128, v250
	v_sub_u32_e32 v130, v210, v176
	v_add_u32_e32 v137, s7, v205
	s_waitcnt lgkmcnt(0)
	v_mov_b64_e32 v[128:129], s[66:67]
	v_ashrrev_i32_e32 v131, 31, v130
	v_mad_i64_i32 v[128:129], s[16:17], v137, s45, v[128:129]
	v_lshl_add_u64 v[128:129], v[130:131], 1, v[128:129]
	v_lshl_add_u64 v[156:157], v[128:129], 0, v[148:149]
	s_nop 1
	v_mov_b32_dpp v136, v135 quad_perm:[1,0,3,2] row_mask:0xf bank_mask:0xf
	v_perm_b32 v141, v136, v135, v250
	s_nop 1
	v_mov_b32_dpp v135, v133 quad_perm:[1,0,3,2] row_mask:0xf bank_mask:0xf
	v_add_co_u32_e32 v138, vcc, 0x22000, v128
	s_nop 1
	v_addc_co_u32_e32 v139, vcc, 0, v129, vcc
	v_perm_b32 v142, v135, v133, v250
	s_nop 1
	v_mov_b32_dpp v133, v132 quad_perm:[1,0,3,2] row_mask:0xf bank_mask:0xf
	v_add_co_u32_e32 v138, vcc, 0x44000, v128
	s_nop 1
	v_addc_co_u32_e32 v139, vcc, 0, v129, vcc
	s_waitcnt lgkmcnt(0)
	v_perm_b32 v143, v133, v132, v250
	v_add_co_u32_e32 v132, vcc, 0x66000, v128
	s_nop 1
	v_addc_co_u32_e32 v133, vcc, 0, v129, vcc
	v_cndmask_b32_e64 v144, v141, v140, s[98:99]
	v_cndmask_b32_e64 v145, v143, v142, s[98:99]
	s_nop 0
	v_mov_b32_dpp v146, v144 quad_perm:[2,3,0,1] row_mask:0xf bank_mask:0xf
	v_mov_b32_dpp v147, v145 quad_perm:[2,3,0,1] row_mask:0xf bank_mask:0xf
	v_cndmask_b32_e64 v152, v140, v146, s[98:99]
	v_cndmask_b32_e64 v153, v146, v141, s[98:99]
	v_lshl_add_u64 v[158:159], v[156:157], 0, v[150:151]
	v_cndmask_b32_e64 v154, v142, v147, s[98:99]
	v_cndmask_b32_e64 v155, v147, v143, s[98:99]
	global_store_dwordx2 v[156:157], v[152:153], off
	global_store_dwordx2 v[158:159], v[154:155], off
	v_cvt_pk_bf16_f32 v136, v116, v117
	s_nop 1
	v_mov_b32_dpp v138, v136 quad_perm:[1,0,3,2] row_mask:0xf bank_mask:0xf
	v_cvt_pk_bf16_f32 v135, v118, v119
	v_cvt_pk_bf16_f32 v133, v112, v113
	v_cvt_pk_bf16_f32 v132, v114, v115
	v_perm_b32 v140, v138, v136, v250
	v_add_u32_e32 v136, s7, v206
	s_waitcnt lgkmcnt(0)
	v_mov_b64_e32 v[138:139], s[66:67]
	v_mad_i64_i32 v[138:139], s[16:17], v136, s45, v[138:139]
	s_nop 1
	v_mov_b32_dpp v136, v135 quad_perm:[1,0,3,2] row_mask:0xf bank_mask:0xf
	v_lshl_add_u64 v[130:131], v[130:131], 1, v[138:139]
	v_lshl_add_u64 v[156:157], v[130:131], 0, v[148:149]
	v_perm_b32 v141, v136, v135, v250
	s_nop 1
	v_mov_b32_dpp v135, v133 quad_perm:[1,0,3,2] row_mask:0xf bank_mask:0xf
	v_add_co_u32_e32 v138, vcc, 0x22000, v130
	s_nop 1
	v_addc_co_u32_e32 v139, vcc, 0, v131, vcc
	v_perm_b32 v142, v135, v133, v250
	s_nop 1
	v_mov_b32_dpp v133, v132 quad_perm:[1,0,3,2] row_mask:0xf bank_mask:0xf
	v_add_co_u32_e32 v138, vcc, 0x44000, v130
	s_nop 1
	v_addc_co_u32_e32 v139, vcc, 0, v131, vcc
	s_waitcnt lgkmcnt(0)
	v_perm_b32 v143, v133, v132, v250
	v_add_co_u32_e32 v132, vcc, 0x66000, v130
	s_nop 1
	v_addc_co_u32_e32 v133, vcc, 0, v131, vcc
	v_cndmask_b32_e64 v144, v141, v140, s[98:99]
	v_cndmask_b32_e64 v145, v143, v142, s[98:99]
	s_nop 0
	v_mov_b32_dpp v146, v144 quad_perm:[2,3,0,1] row_mask:0xf bank_mask:0xf
	v_mov_b32_dpp v147, v145 quad_perm:[2,3,0,1] row_mask:0xf bank_mask:0xf
	v_cndmask_b32_e64 v152, v140, v146, s[98:99]
	v_cndmask_b32_e64 v153, v146, v141, s[98:99]
	v_lshl_add_u64 v[158:159], v[156:157], 0, v[150:151]
	v_cndmask_b32_e64 v154, v142, v147, s[98:99]
	v_cndmask_b32_e64 v155, v147, v143, s[98:99]
	global_store_dwordx2 v[156:157], v[152:153], off
	global_store_dwordx2 v[158:159], v[154:155], off
	v_cvt_pk_bf16_f32 v133, v108, v109
	s_nop 1
	v_mov_b32_dpp v138, v133 quad_perm:[1,0,3,2] row_mask:0xf bank_mask:0xf
	v_cvt_pk_bf16_f32 v132, v110, v111
	v_cvt_pk_bf16_f32 v136, v104, v105
	v_cvt_pk_bf16_f32 v135, v106, v107
	v_perm_b32 v140, v138, v133, v250
	s_nop 1
	v_mov_b32_dpp v133, v132 quad_perm:[1,0,3,2] row_mask:0xf bank_mask:0xf
	v_lshl_add_u64 v[156:157], v[128:129], 0, v[148:149]
	v_perm_b32 v141, v133, v132, v250
	s_waitcnt lgkmcnt(0)
	v_lshl_add_u64 v[132:133], v[128:129], 0, 32
	v_add_co_u32_e32 v138, vcc, 0x22000, v132
	s_nop 1
	v_addc_co_u32_e32 v139, vcc, 0, v133, vcc
	s_nop 1
	v_mov_b32_dpp v137, v136 quad_perm:[1,0,3,2] row_mask:0xf bank_mask:0xf
	v_perm_b32 v142, v137, v136, v250
	v_add_co_u32_e32 v136, vcc, 0x44000, v132
	s_waitcnt lgkmcnt(0)
	s_nop 0
	v_addc_co_u32_e32 v137, vcc, 0, v133, vcc
	s_nop 1
	v_mov_b32_dpp v136, v135 quad_perm:[1,0,3,2] row_mask:0xf bank_mask:0xf
	v_perm_b32 v143, v136, v135, v250
	v_add_co_u32_e32 v132, vcc, 0x66000, v132
	s_nop 1
	v_addc_co_u32_e32 v133, vcc, 0, v133, vcc
	v_cndmask_b32_e64 v144, v141, v140, s[98:99]
	v_cndmask_b32_e64 v145, v143, v142, s[98:99]
	s_nop 0
	v_mov_b32_dpp v146, v144 quad_perm:[2,3,0,1] row_mask:0xf bank_mask:0xf
	v_mov_b32_dpp v147, v145 quad_perm:[2,3,0,1] row_mask:0xf bank_mask:0xf
	v_cndmask_b32_e64 v152, v140, v146, s[98:99]
	v_cndmask_b32_e64 v153, v146, v141, s[98:99]
	v_lshl_add_u64 v[158:159], v[156:157], 0, v[150:151]
	v_cndmask_b32_e64 v154, v142, v147, s[98:99]
	v_cndmask_b32_e64 v155, v147, v143, s[98:99]
	global_store_dwordx2 v[156:157], v[152:153], off offset:32
	global_store_dwordx2 v[158:159], v[154:155], off offset:32
	v_cvt_pk_bf16_f32 v133, v100, v101
	s_nop 1
	v_mov_b32_dpp v138, v133 quad_perm:[1,0,3,2] row_mask:0xf bank_mask:0xf
	v_cvt_pk_bf16_f32 v132, v102, v103
	s_waitcnt lgkmcnt(0)
; __device__ __forceinline__ unsigned cvt_pk_bf16(float lo, float hi) { unsigned r; asm volatile("v_cvt_pk_bf16_f32 %0, %1, %2" : "=v"(r) : "v"(lo), "v"(hi)); return r; }
;     __device__ __forceinline__ void operator()(const f32x4 (&acc)[2][2][4][2], const Unit& u, int wr, int wc, int fr, int fq) const {
;     ...
;                 for (int m = 0; m < 4; ++m) { const int tokrow = row0 + ai * HALF + m * 16;
; #pragma unroll
;                     for (int bj = 0; bj < 2; ++bj) {
;                         const f32x4 v0 = acc[ai][bj][m][0], v1 = acc[ai][bj][m][1];
;                         u32x4 w; w.x = cvt_pk_bf16(v0[0], v0[1]); w.y = cvt_pk_bf16(v0[2], v0[3]); w.z = cvt_pk_bf16(v1[0], v1[1]); w.w = cvt_pk_bf16(v1[2], v1[3]);
;                         bf16_t* vt = KT + (size_t)(512 + (u.pn - 12) * BM + bj * HALF + wc * 32 + 8 * fq + odd) * ldk + (tokrow - odd);
; #pragma unroll
;                         for (int q = 0; q < 4; ++q) { const unsigned mine = w[q], other = (unsigned)__shfl_xor((int)mine, 1);
;                             const unsigned pr = odd ? ((other >> 16) | (mine & 0xffff0000u)) : ((mine & 0xffffu) | (other << 16));
;                             *(unsigned*)(vt + (size_t)(2 * q) * ldk) = pr; }
;                     } }
	v_cvt_pk_bf16_f32 v136, v96, v97
	v_cvt_pk_bf16_f32 v135, v98, v99
	v_perm_b32 v140, v138, v133, v250
	s_nop 1
	v_mov_b32_dpp v133, v132 quad_perm:[1,0,3,2] row_mask:0xf bank_mask:0xf
	v_lshl_add_u64 v[156:157], v[130:131], 0, v[148:149]
	v_perm_b32 v141, v133, v132, v250
	s_waitcnt lgkmcnt(0)
	v_lshl_add_u64 v[132:133], v[130:131], 0, 32
	v_add_co_u32_e32 v138, vcc, 0x22000, v132
	s_nop 1
	v_addc_co_u32_e32 v139, vcc, 0, v133, vcc
	s_nop 1
	v_mov_b32_dpp v137, v136 quad_perm:[1,0,3,2] row_mask:0xf bank_mask:0xf
	v_perm_b32 v142, v137, v136, v250
	v_add_co_u32_e32 v136, vcc, 0x44000, v132
	s_waitcnt lgkmcnt(0)
	s_nop 0
	v_addc_co_u32_e32 v137, vcc, 0, v133, vcc
	s_nop 1
	v_mov_b32_dpp v136, v135 quad_perm:[1,0,3,2] row_mask:0xf bank_mask:0xf
	v_perm_b32 v143, v136, v135, v250
	v_add_co_u32_e32 v132, vcc, 0x66000, v132
	s_nop 1
	v_addc_co_u32_e32 v133, vcc, 0, v133, vcc
	v_cndmask_b32_e64 v144, v141, v140, s[98:99]
	v_cndmask_b32_e64 v145, v143, v142, s[98:99]
	s_nop 0
	v_mov_b32_dpp v146, v144 quad_perm:[2,3,0,1] row_mask:0xf bank_mask:0xf
	v_mov_b32_dpp v147, v145 quad_perm:[2,3,0,1] row_mask:0xf bank_mask:0xf
	v_cndmask_b32_e64 v152, v140, v146, s[98:99]
	v_cndmask_b32_e64 v153, v146, v141, s[98:99]
	v_lshl_add_u64 v[158:159], v[156:157], 0, v[150:151]
	v_cndmask_b32_e64 v154, v142, v147, s[98:99]
	v_cndmask_b32_e64 v155, v147, v143, s[98:99]
	global_store_dwordx2 v[156:157], v[152:153], off offset:32
	global_store_dwordx2 v[158:159], v[154:155], off offset:32
	v_cvt_pk_bf16_f32 v133, v92, v93
	s_nop 1
	v_mov_b32_dpp v138, v133 quad_perm:[1,0,3,2] row_mask:0xf bank_mask:0xf
	v_cvt_pk_bf16_f32 v132, v94, v95
	s_waitcnt lgkmcnt(0)
	v_cvt_pk_bf16_f32 v136, v88, v89
	v_cvt_pk_bf16_f32 v135, v90, v91
	v_perm_b32 v140, v138, v133, v250
	s_nop 1
	v_mov_b32_dpp v133, v132 quad_perm:[1,0,3,2] row_mask:0xf bank_mask:0xf
	v_lshl_add_u64 v[156:157], v[128:129], 0, v[148:149]
	v_perm_b32 v141, v133, v132, v250
	s_waitcnt lgkmcnt(0)
	v_lshl_add_u64 v[132:133], v[128:129], 0, 64
	v_add_co_u32_e32 v138, vcc, 0x22000, v132
	s_nop 1
	v_addc_co_u32_e32 v139, vcc, 0, v133, vcc
	s_nop 1
	v_mov_b32_dpp v137, v136 quad_perm:[1,0,3,2] row_mask:0xf bank_mask:0xf
	v_perm_b32 v142, v137, v136, v250
	v_add_co_u32_e32 v136, vcc, 0x44000, v132
	s_waitcnt lgkmcnt(0)
	s_nop 0
	v_addc_co_u32_e32 v137, vcc, 0, v133, vcc
	s_nop 1
	v_mov_b32_dpp v136, v135 quad_perm:[1,0,3,2] row_mask:0xf bank_mask:0xf
	v_perm_b32 v143, v136, v135, v250
	v_add_co_u32_e32 v132, vcc, 0x66000, v132
	s_nop 1
	v_addc_co_u32_e32 v133, vcc, 0, v133, vcc
	v_cndmask_b32_e64 v144, v141, v140, s[98:99]
	v_cndmask_b32_e64 v145, v143, v142, s[98:99]
	s_nop 0
	v_mov_b32_dpp v146, v144 quad_perm:[2,3,0,1] row_mask:0xf bank_mask:0xf
	v_mov_b32_dpp v147, v145 quad_perm:[2,3,0,1] row_mask:0xf bank_mask:0xf
	v_cndmask_b32_e64 v152, v140, v146, s[98:99]
	v_cndmask_b32_e64 v153, v146, v141, s[98:99]
	v_lshl_add_u64 v[158:159], v[156:157], 0, v[150:151]
	v_cndmask_b32_e64 v154, v142, v147, s[98:99]
	v_cndmask_b32_e64 v155, v147, v143, s[98:99]
	global_store_dwordx2 v[156:157], v[152:153], off offset:64
	global_store_dwordx2 v[158:159], v[154:155], off offset:64
	v_cvt_pk_bf16_f32 v133, v84, v85
	s_nop 1
	v_mov_b32_dpp v138, v133 quad_perm:[1,0,3,2] row_mask:0xf bank_mask:0xf
	v_cvt_pk_bf16_f32 v132, v86, v87
	s_waitcnt lgkmcnt(0)
	v_cvt_pk_bf16_f32 v136, v80, v81
	v_cvt_pk_bf16_f32 v135, v82, v83
	v_perm_b32 v140, v138, v133, v250
	s_nop 1
	v_mov_b32_dpp v133, v132 quad_perm:[1,0,3,2] row_mask:0xf bank_mask:0xf
	v_lshl_add_u64 v[156:157], v[130:131], 0, v[148:149]
	v_perm_b32 v141, v133, v132, v250
	s_waitcnt lgkmcnt(0)
	v_lshl_add_u64 v[132:133], v[130:131], 0, 64
	v_add_co_u32_e32 v138, vcc, 0x22000, v132
	s_nop 1
	v_addc_co_u32_e32 v139, vcc, 0, v133, vcc
	s_nop 1
	v_mov_b32_dpp v137, v136 quad_perm:[1,0,3,2] row_mask:0xf bank_mask:0xf
	v_perm_b32 v142, v137, v136, v250
	v_add_co_u32_e32 v136, vcc, 0x44000, v132
	s_waitcnt lgkmcnt(0)
	s_nop 0
	v_addc_co_u32_e32 v137, vcc, 0, v133, vcc
	s_nop 1
	v_mov_b32_dpp v136, v135 quad_perm:[1,0,3,2] row_mask:0xf bank_mask:0xf
	v_perm_b32 v143, v136, v135, v250
	v_add_co_u32_e32 v132, vcc, 0x66000, v132
	s_nop 1
	v_addc_co_u32_e32 v133, vcc, 0, v133, vcc
	v_cndmask_b32_e64 v144, v141, v140, s[98:99]
	v_cndmask_b32_e64 v145, v143, v142, s[98:99]
	s_nop 0
	v_mov_b32_dpp v146, v144 quad_perm:[2,3,0,1] row_mask:0xf bank_mask:0xf
	v_mov_b32_dpp v147, v145 quad_perm:[2,3,0,1] row_mask:0xf bank_mask:0xf
	v_cndmask_b32_e64 v152, v140, v146, s[98:99]
	v_cndmask_b32_e64 v153, v146, v141, s[98:99]
	v_lshl_add_u64 v[158:159], v[156:157], 0, v[150:151]
	v_cndmask_b32_e64 v154, v142, v147, s[98:99]
	v_cndmask_b32_e64 v155, v147, v143, s[98:99]
	global_store_dwordx2 v[156:157], v[152:153], off offset:64
	global_store_dwordx2 v[158:159], v[154:155], off offset:64
	v_cvt_pk_bf16_f32 v133, v76, v77
	s_nop 1
	v_mov_b32_dpp v138, v133 quad_perm:[1,0,3,2] row_mask:0xf bank_mask:0xf
	v_cvt_pk_bf16_f32 v132, v78, v79
	s_waitcnt lgkmcnt(0)
	v_cvt_pk_bf16_f32 v136, v72, v73
	v_cvt_pk_bf16_f32 v135, v74, v75
	v_perm_b32 v140, v138, v133, v250
	s_nop 1
	v_mov_b32_dpp v133, v132 quad_perm:[1,0,3,2] row_mask:0xf bank_mask:0xf
	v_lshl_add_u64 v[156:157], v[128:129], 0, v[148:149]
	v_perm_b32 v141, v133, v132, v250
	s_waitcnt lgkmcnt(0)
	v_lshl_add_u64 v[132:133], v[128:129], 0, s[36:37]
	v_add_co_u32_e32 v138, vcc, 0x22000, v132
	s_nop 1
	v_addc_co_u32_e32 v139, vcc, 0, v133, vcc
	s_nop 1
	v_mov_b32_dpp v137, v136 quad_perm:[1,0,3,2] row_mask:0xf bank_mask:0xf
	v_perm_b32 v142, v137, v136, v250
	v_add_co_u32_e32 v136, vcc, 0x44000, v132
	s_waitcnt lgkmcnt(0)
; __device__ __forceinline__ unsigned cvt_pk_bf16(float lo, float hi) { unsigned r; asm volatile("v_cvt_pk_bf16_f32 %0, %1, %2" : "=v"(r) : "v"(lo), "v"(hi)); return r; }
;     __device__ __forceinline__ void operator()(const f32x4 (&acc)[2][2][4][2], const Unit& u, int wr, int wc, int fr, int fq) const {
;     ...
;                         u32x4 w; w.x = cvt_pk_bf16(v0[0], v0[1]); w.y = cvt_pk_bf16(v0[2], v0[3]); w.z = cvt_pk_bf16(v1[0], v1[1]); w.w = cvt_pk_bf16(v1[2], v1[3]);
;                         bf16_t* vt = KT + (size_t)(512 + (u.pn - 12) * BM + bj * HALF + wc * 32 + 8 * fq + odd) * ldk + (tokrow - odd);
; #pragma unroll
;                         for (int q = 0; q < 4; ++q) { const unsigned mine = w[q], other = (unsigned)__shfl_xor((int)mine, 1);
;                             const unsigned pr = odd ? ((other >> 16) | (mine & 0xffff0000u)) : ((mine & 0xffffu) | (other << 16));
;                             *(unsigned*)(vt + (size_t)(2 * q) * ldk) = pr; }
	s_nop 0
	v_addc_co_u32_e32 v137, vcc, 0, v133, vcc
	s_nop 1
	v_mov_b32_dpp v136, v135 quad_perm:[1,0,3,2] row_mask:0xf bank_mask:0xf
	v_perm_b32 v143, v136, v135, v250
	v_add_co_u32_e32 v132, vcc, 0x66000, v132
	s_nop 1
	v_addc_co_u32_e32 v133, vcc, 0, v133, vcc
	v_cndmask_b32_e64 v144, v141, v140, s[98:99]
	v_cndmask_b32_e64 v145, v143, v142, s[98:99]
	s_nop 0
	v_mov_b32_dpp v146, v144 quad_perm:[2,3,0,1] row_mask:0xf bank_mask:0xf
	v_mov_b32_dpp v147, v145 quad_perm:[2,3,0,1] row_mask:0xf bank_mask:0xf
	v_cndmask_b32_e64 v152, v140, v146, s[98:99]
	v_cndmask_b32_e64 v153, v146, v141, s[98:99]
	v_lshl_add_u64 v[158:159], v[156:157], 0, v[150:151]
	v_cndmask_b32_e64 v154, v142, v147, s[98:99]
	v_cndmask_b32_e64 v155, v147, v143, s[98:99]
	global_store_dwordx2 v[156:157], v[152:153], off offset:96
	global_store_dwordx2 v[158:159], v[154:155], off offset:96
	v_cvt_pk_bf16_f32 v133, v68, v69
	s_nop 1
	v_mov_b32_dpp v138, v133 quad_perm:[1,0,3,2] row_mask:0xf bank_mask:0xf
	v_cvt_pk_bf16_f32 v132, v70, v71
	s_waitcnt lgkmcnt(0)
	v_cvt_pk_bf16_f32 v136, v64, v65
	v_cvt_pk_bf16_f32 v135, v66, v67
	v_perm_b32 v140, v138, v133, v250
	s_nop 1
	v_mov_b32_dpp v133, v132 quad_perm:[1,0,3,2] row_mask:0xf bank_mask:0xf
	v_lshl_add_u64 v[156:157], v[130:131], 0, v[148:149]
	v_perm_b32 v141, v133, v132, v250
	s_waitcnt lgkmcnt(0)
	v_lshl_add_u64 v[132:133], v[130:131], 0, s[36:37]
	v_add_co_u32_e32 v138, vcc, 0x22000, v132
	s_nop 1
	v_addc_co_u32_e32 v139, vcc, 0, v133, vcc
	s_nop 1
	v_mov_b32_dpp v137, v136 quad_perm:[1,0,3,2] row_mask:0xf bank_mask:0xf
	v_perm_b32 v142, v137, v136, v250
	v_add_co_u32_e32 v136, vcc, 0x44000, v132
	s_waitcnt lgkmcnt(0)
	s_nop 0
	v_addc_co_u32_e32 v137, vcc, 0, v133, vcc
	s_nop 1
	v_mov_b32_dpp v136, v135 quad_perm:[1,0,3,2] row_mask:0xf bank_mask:0xf
	v_perm_b32 v143, v136, v135, v250
	v_add_co_u32_e32 v132, vcc, 0x66000, v132
	s_nop 1
	v_addc_co_u32_e32 v133, vcc, 0, v133, vcc
	v_cndmask_b32_e64 v144, v141, v140, s[98:99]
	v_cndmask_b32_e64 v145, v143, v142, s[98:99]
	s_nop 0
	v_mov_b32_dpp v146, v144 quad_perm:[2,3,0,1] row_mask:0xf bank_mask:0xf
	v_mov_b32_dpp v147, v145 quad_perm:[2,3,0,1] row_mask:0xf bank_mask:0xf
	v_cndmask_b32_e64 v152, v140, v146, s[98:99]
	v_cndmask_b32_e64 v153, v146, v141, s[98:99]
	v_lshl_add_u64 v[158:159], v[156:157], 0, v[150:151]
	v_cndmask_b32_e64 v154, v142, v147, s[98:99]
	v_cndmask_b32_e64 v155, v147, v143, s[98:99]
	global_store_dwordx2 v[156:157], v[152:153], off offset:96
	global_store_dwordx2 v[158:159], v[154:155], off offset:96
	v_cvt_pk_bf16_f32 v133, v60, v61
	s_nop 1
	v_mov_b32_dpp v138, v133 quad_perm:[1,0,3,2] row_mask:0xf bank_mask:0xf
	v_cvt_pk_bf16_f32 v132, v62, v63
	s_waitcnt lgkmcnt(0)
	v_cvt_pk_bf16_f32 v136, v56, v57
	v_cvt_pk_bf16_f32 v135, v58, v59
	v_perm_b32 v140, v138, v133, v250
	s_nop 1
	v_mov_b32_dpp v133, v132 quad_perm:[1,0,3,2] row_mask:0xf bank_mask:0xf
	v_lshl_add_u64 v[156:157], v[128:129], 0, v[148:149]
	v_perm_b32 v141, v133, v132, v250
	s_mov_b64 s[16:17], 0x100
	s_waitcnt lgkmcnt(0)
	v_lshl_add_u64 v[132:133], v[128:129], 0, s[16:17]
	v_add_co_u32_e32 v138, vcc, 0x22000, v132
	s_nop 1
	v_addc_co_u32_e32 v139, vcc, 0, v133, vcc
	s_nop 1
	v_mov_b32_dpp v137, v136 quad_perm:[1,0,3,2] row_mask:0xf bank_mask:0xf
	v_perm_b32 v142, v137, v136, v250
	v_add_co_u32_e32 v136, vcc, 0x44000, v132
	s_waitcnt lgkmcnt(0)
	s_nop 0
	v_addc_co_u32_e32 v137, vcc, 0, v133, vcc
	s_nop 1
	v_mov_b32_dpp v136, v135 quad_perm:[1,0,3,2] row_mask:0xf bank_mask:0xf
	v_perm_b32 v143, v136, v135, v250
	v_add_co_u32_e32 v132, vcc, 0x66000, v132
	s_nop 1
	v_addc_co_u32_e32 v133, vcc, 0, v133, vcc
	v_cndmask_b32_e64 v144, v141, v140, s[98:99]
	v_cndmask_b32_e64 v145, v143, v142, s[98:99]
	s_nop 0
	v_mov_b32_dpp v146, v144 quad_perm:[2,3,0,1] row_mask:0xf bank_mask:0xf
	v_mov_b32_dpp v147, v145 quad_perm:[2,3,0,1] row_mask:0xf bank_mask:0xf
	v_cndmask_b32_e64 v152, v140, v146, s[98:99]
	v_cndmask_b32_e64 v153, v146, v141, s[98:99]
	v_lshl_add_u64 v[158:159], v[156:157], 0, v[150:151]
	v_cndmask_b32_e64 v154, v142, v147, s[98:99]
	v_cndmask_b32_e64 v155, v147, v143, s[98:99]
	global_store_dwordx2 v[156:157], v[152:153], off offset:256
	global_store_dwordx2 v[158:159], v[154:155], off offset:256
	v_cvt_pk_bf16_f32 v133, v52, v53
	s_nop 1
	v_mov_b32_dpp v138, v133 quad_perm:[1,0,3,2] row_mask:0xf bank_mask:0xf
	v_cvt_pk_bf16_f32 v132, v54, v55
	s_waitcnt lgkmcnt(0)
	v_cvt_pk_bf16_f32 v136, v48, v49
	v_cvt_pk_bf16_f32 v135, v50, v51
	v_perm_b32 v140, v138, v133, v250
	s_nop 1
	v_mov_b32_dpp v133, v132 quad_perm:[1,0,3,2] row_mask:0xf bank_mask:0xf
	v_lshl_add_u64 v[156:157], v[130:131], 0, v[148:149]
	v_perm_b32 v141, v133, v132, v250
	s_mov_b64 s[16:17], 0x100
	s_waitcnt lgkmcnt(0)
	v_lshl_add_u64 v[132:133], v[130:131], 0, s[16:17]
	v_add_co_u32_e32 v138, vcc, 0x22000, v132
	s_nop 1
	v_addc_co_u32_e32 v139, vcc, 0, v133, vcc
	s_nop 1
	v_mov_b32_dpp v137, v136 quad_perm:[1,0,3,2] row_mask:0xf bank_mask:0xf
	v_perm_b32 v142, v137, v136, v250
	v_add_co_u32_e32 v136, vcc, 0x44000, v132
	s_waitcnt lgkmcnt(0)
	s_nop 0
	v_addc_co_u32_e32 v137, vcc, 0, v133, vcc
	s_nop 1
	v_mov_b32_dpp v136, v135 quad_perm:[1,0,3,2] row_mask:0xf bank_mask:0xf
	v_perm_b32 v143, v136, v135, v250
	v_add_co_u32_e32 v132, vcc, 0x66000, v132
	s_nop 1
	v_addc_co_u32_e32 v133, vcc, 0, v133, vcc
	v_cndmask_b32_e64 v144, v141, v140, s[98:99]
	v_cndmask_b32_e64 v145, v143, v142, s[98:99]
	s_nop 0
	v_mov_b32_dpp v146, v144 quad_perm:[2,3,0,1] row_mask:0xf bank_mask:0xf
	v_mov_b32_dpp v147, v145 quad_perm:[2,3,0,1] row_mask:0xf bank_mask:0xf
	v_cndmask_b32_e64 v152, v140, v146, s[98:99]
	v_cndmask_b32_e64 v153, v146, v141, s[98:99]
	v_lshl_add_u64 v[158:159], v[156:157], 0, v[150:151]
	v_cndmask_b32_e64 v154, v142, v147, s[98:99]
	v_cndmask_b32_e64 v155, v147, v143, s[98:99]
	global_store_dwordx2 v[156:157], v[152:153], off offset:256
	global_store_dwordx2 v[158:159], v[154:155], off offset:256
	v_cvt_pk_bf16_f32 v133, v44, v45
	s_nop 1
	v_mov_b32_dpp v138, v133 quad_perm:[1,0,3,2] row_mask:0xf bank_mask:0xf
	v_cvt_pk_bf16_f32 v132, v46, v47
	s_waitcnt lgkmcnt(0)
; __device__ __forceinline__ unsigned cvt_pk_bf16(float lo, float hi) { unsigned r; asm volatile("v_cvt_pk_bf16_f32 %0, %1, %2" : "=v"(r) : "v"(lo), "v"(hi)); return r; }
;     __device__ __forceinline__ void operator()(const f32x4 (&acc)[2][2][4][2], const Unit& u, int wr, int wc, int fr, int fq) const {
;     ...
;                         u32x4 w; w.x = cvt_pk_bf16(v0[0], v0[1]); w.y = cvt_pk_bf16(v0[2], v0[3]); w.z = cvt_pk_bf16(v1[0], v1[1]); w.w = cvt_pk_bf16(v1[2], v1[3]);
;                         bf16_t* vt = KT + (size_t)(512 + (u.pn - 12) * BM + bj * HALF + wc * 32 + 8 * fq + odd) * ldk + (tokrow - odd);
; #pragma unroll
;                         for (int q = 0; q < 4; ++q) { const unsigned mine = w[q], other = (unsigned)__shfl_xor((int)mine, 1);
;                             const unsigned pr = odd ? ((other >> 16) | (mine & 0xffff0000u)) : ((mine & 0xffffu) | (other << 16));
;                             *(unsigned*)(vt + (size_t)(2 * q) * ldk) = pr; }
	v_cvt_pk_bf16_f32 v136, v40, v41
	v_cvt_pk_bf16_f32 v135, v42, v43
	v_perm_b32 v140, v138, v133, v250
	s_nop 1
	v_mov_b32_dpp v133, v132 quad_perm:[1,0,3,2] row_mask:0xf bank_mask:0xf
	v_lshl_add_u64 v[156:157], v[128:129], 0, v[148:149]
	v_perm_b32 v141, v133, v132, v250
	s_waitcnt lgkmcnt(0)
	v_lshl_add_u64 v[132:133], v[128:129], 0, s[38:39]
	v_add_co_u32_e32 v138, vcc, 0x22000, v132
	s_nop 1
	v_addc_co_u32_e32 v139, vcc, 0, v133, vcc
	s_nop 1
	v_mov_b32_dpp v137, v136 quad_perm:[1,0,3,2] row_mask:0xf bank_mask:0xf
	v_perm_b32 v142, v137, v136, v250
	v_add_co_u32_e32 v136, vcc, 0x44000, v132
	s_waitcnt lgkmcnt(0)
	s_nop 0
	v_addc_co_u32_e32 v137, vcc, 0, v133, vcc
	s_nop 1
	v_mov_b32_dpp v136, v135 quad_perm:[1,0,3,2] row_mask:0xf bank_mask:0xf
	v_perm_b32 v143, v136, v135, v250
	v_add_co_u32_e32 v132, vcc, 0x66000, v132
	s_nop 1
	v_addc_co_u32_e32 v133, vcc, 0, v133, vcc
	v_cndmask_b32_e64 v144, v141, v140, s[98:99]
	v_cndmask_b32_e64 v145, v143, v142, s[98:99]
	s_nop 0
	v_mov_b32_dpp v146, v144 quad_perm:[2,3,0,1] row_mask:0xf bank_mask:0xf
	v_mov_b32_dpp v147, v145 quad_perm:[2,3,0,1] row_mask:0xf bank_mask:0xf
	v_cndmask_b32_e64 v152, v140, v146, s[98:99]
	v_cndmask_b32_e64 v153, v146, v141, s[98:99]
	v_lshl_add_u64 v[158:159], v[156:157], 0, v[150:151]
	v_cndmask_b32_e64 v154, v142, v147, s[98:99]
	v_cndmask_b32_e64 v155, v147, v143, s[98:99]
	global_store_dwordx2 v[156:157], v[152:153], off offset:288
	global_store_dwordx2 v[158:159], v[154:155], off offset:288
	v_cvt_pk_bf16_f32 v133, v36, v37
	s_nop 1
	v_mov_b32_dpp v138, v133 quad_perm:[1,0,3,2] row_mask:0xf bank_mask:0xf
	v_cvt_pk_bf16_f32 v132, v38, v39
	s_waitcnt lgkmcnt(0)
	v_cvt_pk_bf16_f32 v136, v32, v33
	v_cvt_pk_bf16_f32 v135, v34, v35
	v_perm_b32 v140, v138, v133, v250
	s_nop 1
	v_mov_b32_dpp v133, v132 quad_perm:[1,0,3,2] row_mask:0xf bank_mask:0xf
	v_lshl_add_u64 v[156:157], v[130:131], 0, v[148:149]
	v_perm_b32 v141, v133, v132, v250
	s_waitcnt lgkmcnt(0)
	v_lshl_add_u64 v[132:133], v[130:131], 0, s[38:39]
	v_add_co_u32_e32 v138, vcc, 0x22000, v132
	s_nop 1
	v_addc_co_u32_e32 v139, vcc, 0, v133, vcc
	s_nop 1
	v_mov_b32_dpp v137, v136 quad_perm:[1,0,3,2] row_mask:0xf bank_mask:0xf
	v_perm_b32 v142, v137, v136, v250
	v_add_co_u32_e32 v136, vcc, 0x44000, v132
	s_waitcnt lgkmcnt(0)
	s_nop 0
	v_addc_co_u32_e32 v137, vcc, 0, v133, vcc
	s_nop 1
	v_mov_b32_dpp v136, v135 quad_perm:[1,0,3,2] row_mask:0xf bank_mask:0xf
	v_perm_b32 v143, v136, v135, v250
	v_add_co_u32_e32 v132, vcc, 0x66000, v132
	s_nop 1
	v_addc_co_u32_e32 v133, vcc, 0, v133, vcc
	v_cndmask_b32_e64 v144, v141, v140, s[98:99]
	v_cndmask_b32_e64 v145, v143, v142, s[98:99]
	s_nop 0
	v_mov_b32_dpp v146, v144 quad_perm:[2,3,0,1] row_mask:0xf bank_mask:0xf
	v_mov_b32_dpp v147, v145 quad_perm:[2,3,0,1] row_mask:0xf bank_mask:0xf
	v_cndmask_b32_e64 v152, v140, v146, s[98:99]
	v_cndmask_b32_e64 v153, v146, v141, s[98:99]
	v_lshl_add_u64 v[158:159], v[156:157], 0, v[150:151]
	v_cndmask_b32_e64 v154, v142, v147, s[98:99]
	v_cndmask_b32_e64 v155, v147, v143, s[98:99]
	global_store_dwordx2 v[156:157], v[152:153], off offset:288
	global_store_dwordx2 v[158:159], v[154:155], off offset:288
	v_cvt_pk_bf16_f32 v133, v28, v29
	s_nop 1
	v_mov_b32_dpp v138, v133 quad_perm:[1,0,3,2] row_mask:0xf bank_mask:0xf
	v_cvt_pk_bf16_f32 v132, v30, v31
	s_waitcnt lgkmcnt(0)
	v_cvt_pk_bf16_f32 v136, v24, v25
	v_cvt_pk_bf16_f32 v135, v26, v27
	v_perm_b32 v140, v138, v133, v250
	s_nop 1
	v_mov_b32_dpp v133, v132 quad_perm:[1,0,3,2] row_mask:0xf bank_mask:0xf
	v_lshl_add_u64 v[156:157], v[128:129], 0, v[148:149]
	v_perm_b32 v141, v133, v132, v250
	s_waitcnt lgkmcnt(0)
	v_lshl_add_u64 v[132:133], v[128:129], 0, s[40:41]
	v_add_co_u32_e32 v138, vcc, 0x22000, v132
	s_nop 1
	v_addc_co_u32_e32 v139, vcc, 0, v133, vcc
	s_nop 1
	v_mov_b32_dpp v137, v136 quad_perm:[1,0,3,2] row_mask:0xf bank_mask:0xf
	v_perm_b32 v142, v137, v136, v250
	v_add_co_u32_e32 v136, vcc, 0x44000, v132
	s_waitcnt lgkmcnt(0)
	s_nop 0
	v_addc_co_u32_e32 v137, vcc, 0, v133, vcc
	s_nop 1
	v_mov_b32_dpp v136, v135 quad_perm:[1,0,3,2] row_mask:0xf bank_mask:0xf
	v_perm_b32 v143, v136, v135, v250
	v_add_co_u32_e32 v132, vcc, 0x66000, v132
	s_nop 1
	v_addc_co_u32_e32 v133, vcc, 0, v133, vcc
	v_cndmask_b32_e64 v144, v141, v140, s[98:99]
	v_cndmask_b32_e64 v145, v143, v142, s[98:99]
	s_nop 0
	v_mov_b32_dpp v146, v144 quad_perm:[2,3,0,1] row_mask:0xf bank_mask:0xf
	v_mov_b32_dpp v147, v145 quad_perm:[2,3,0,1] row_mask:0xf bank_mask:0xf
	v_cndmask_b32_e64 v152, v140, v146, s[98:99]
	v_cndmask_b32_e64 v153, v146, v141, s[98:99]
	v_lshl_add_u64 v[158:159], v[156:157], 0, v[150:151]
	v_cndmask_b32_e64 v154, v142, v147, s[98:99]
	v_cndmask_b32_e64 v155, v147, v143, s[98:99]
	global_store_dwordx2 v[156:157], v[152:153], off offset:320
	global_store_dwordx2 v[158:159], v[154:155], off offset:320
	v_cvt_pk_bf16_f32 v133, v20, v21
	s_nop 1
	v_mov_b32_dpp v138, v133 quad_perm:[1,0,3,2] row_mask:0xf bank_mask:0xf
	v_cvt_pk_bf16_f32 v132, v22, v23
	s_waitcnt lgkmcnt(0)
; __device__ __forceinline__ unsigned cvt_pk_bf16(float lo, float hi) { unsigned r; asm volatile("v_cvt_pk_bf16_f32 %0, %1, %2" : "=v"(r) : "v"(lo), "v"(hi)); return r; }
;     __device__ __forceinline__ void operator()(const f32x4 (&acc)[2][2][4][2], const Unit& u, int wr, int wc, int fr, int fq) const {
;     ...
;                         u32x4 w; w.x = cvt_pk_bf16(v0[0], v0[1]); w.y = cvt_pk_bf16(v0[2], v0[3]); w.z = cvt_pk_bf16(v1[0], v1[1]); w.w = cvt_pk_bf16(v1[2], v1[3]);
;                         bf16_t* vt = KT + (size_t)(512 + (u.pn - 12) * BM + bj * HALF + wc * 32 + 8 * fq + odd) * ldk + (tokrow - odd);
; #pragma unroll
;                         for (int q = 0; q < 4; ++q) { const unsigned mine = w[q], other = (unsigned)__shfl_xor((int)mine, 1);
;                             const unsigned pr = odd ? ((other >> 16) | (mine & 0xffff0000u)) : ((mine & 0xffffu) | (other << 16));
;                             *(unsigned*)(vt + (size_t)(2 * q) * ldk) = pr; }
	v_cvt_pk_bf16_f32 v136, v16, v17
	v_cvt_pk_bf16_f32 v135, v18, v19
	v_perm_b32 v140, v138, v133, v250
	s_nop 1
	v_mov_b32_dpp v133, v132 quad_perm:[1,0,3,2] row_mask:0xf bank_mask:0xf
	v_lshl_add_u64 v[156:157], v[130:131], 0, v[148:149]
	v_perm_b32 v141, v133, v132, v250
	s_waitcnt lgkmcnt(0)
	v_lshl_add_u64 v[132:133], v[130:131], 0, s[40:41]
	v_add_co_u32_e32 v138, vcc, 0x22000, v132
	s_nop 1
	v_addc_co_u32_e32 v139, vcc, 0, v133, vcc
	s_nop 1
	v_mov_b32_dpp v137, v136 quad_perm:[1,0,3,2] row_mask:0xf bank_mask:0xf
	v_perm_b32 v142, v137, v136, v250
	v_add_co_u32_e32 v136, vcc, 0x44000, v132
	s_waitcnt lgkmcnt(0)
	s_nop 0
	v_addc_co_u32_e32 v137, vcc, 0, v133, vcc
	s_nop 1
	v_mov_b32_dpp v136, v135 quad_perm:[1,0,3,2] row_mask:0xf bank_mask:0xf
	v_perm_b32 v143, v136, v135, v250
	v_add_co_u32_e32 v132, vcc, 0x66000, v132
	s_nop 1
	v_addc_co_u32_e32 v133, vcc, 0, v133, vcc
	v_cndmask_b32_e64 v144, v141, v140, s[98:99]
	v_cndmask_b32_e64 v145, v143, v142, s[98:99]
	s_nop 0
	v_mov_b32_dpp v146, v144 quad_perm:[2,3,0,1] row_mask:0xf bank_mask:0xf
	v_mov_b32_dpp v147, v145 quad_perm:[2,3,0,1] row_mask:0xf bank_mask:0xf
	v_cndmask_b32_e64 v152, v140, v146, s[98:99]
	v_cndmask_b32_e64 v153, v146, v141, s[98:99]
	v_lshl_add_u64 v[158:159], v[156:157], 0, v[150:151]
	v_cndmask_b32_e64 v154, v142, v147, s[98:99]
	v_cndmask_b32_e64 v155, v147, v143, s[98:99]
	global_store_dwordx2 v[156:157], v[152:153], off offset:320
	global_store_dwordx2 v[158:159], v[154:155], off offset:320
	s_waitcnt lgkmcnt(0)
	v_cvt_pk_bf16_f32 v136, v12, v13
	s_nop 1
	v_mov_b32_dpp v138, v136 quad_perm:[1,0,3,2] row_mask:0xf bank_mask:0xf
	v_cvt_pk_bf16_f32 v135, v14, v15
	v_cvt_pk_bf16_f32 v133, v8, v9
	v_cvt_pk_bf16_f32 v132, v10, v11
	v_perm_b32 v140, v138, v136, v250
	s_waitcnt lgkmcnt(0)
	s_nop 1
	v_mov_b32_dpp v138, v135 quad_perm:[1,0,3,2] row_mask:0xf bank_mask:0xf
	v_lshl_add_u64 v[156:157], v[128:129], 0, v[148:149]
	v_perm_b32 v141, v138, v135, v250
	s_nop 1
	v_mov_b32_dpp v135, v133 quad_perm:[1,0,3,2] row_mask:0xf bank_mask:0xf
	v_lshl_add_u64 v[128:129], v[128:129], 0, s[42:43]
	s_waitcnt lgkmcnt(0)
	v_add_co_u32_e32 v138, vcc, 0x22000, v128
	s_nop 1
	v_addc_co_u32_e32 v139, vcc, 0, v129, vcc
	v_perm_b32 v142, v135, v133, v250
	s_nop 1
	v_mov_b32_dpp v133, v132 quad_perm:[1,0,3,2] row_mask:0xf bank_mask:0xf
	v_add_co_u32_e32 v138, vcc, 0x44000, v128
	s_nop 1
	v_addc_co_u32_e32 v139, vcc, 0, v129, vcc
	v_perm_b32 v143, v133, v132, v250
	v_add_co_u32_e32 v128, vcc, 0x66000, v128
	s_nop 1
	v_addc_co_u32_e32 v129, vcc, 0, v129, vcc
	v_cndmask_b32_e64 v144, v141, v140, s[98:99]
	v_cndmask_b32_e64 v145, v143, v142, s[98:99]
	s_nop 0
	v_mov_b32_dpp v146, v144 quad_perm:[2,3,0,1] row_mask:0xf bank_mask:0xf
	v_mov_b32_dpp v147, v145 quad_perm:[2,3,0,1] row_mask:0xf bank_mask:0xf
	v_cndmask_b32_e64 v152, v140, v146, s[98:99]
	v_cndmask_b32_e64 v153, v146, v141, s[98:99]
	v_lshl_add_u64 v[158:159], v[156:157], 0, v[150:151]
	v_cndmask_b32_e64 v154, v142, v147, s[98:99]
	v_cndmask_b32_e64 v155, v147, v143, s[98:99]
	global_store_dwordx2 v[156:157], v[152:153], off offset:352
	global_store_dwordx2 v[158:159], v[154:155], off offset:352
	v_cvt_pk_bf16_f32 v129, v4, v5
	s_nop 1
	v_mov_b32_dpp v136, v129 quad_perm:[1,0,3,2] row_mask:0xf bank_mask:0xf
	v_cvt_pk_bf16_f32 v128, v6, v7
	s_waitcnt lgkmcnt(0)
	v_cvt_pk_bf16_f32 v133, v0, v1
	v_cvt_pk_bf16_f32 v132, v2, v3
	v_perm_b32 v140, v136, v129, v250
	s_nop 1
	v_mov_b32_dpp v129, v128 quad_perm:[1,0,3,2] row_mask:0xf bank_mask:0xf
	v_lshl_add_u64 v[156:157], v[130:131], 0, v[148:149]
	v_perm_b32 v141, v129, v128, v250
	s_waitcnt lgkmcnt(0)
	v_lshl_add_u64 v[128:129], v[130:131], 0, s[42:43]
	v_add_co_u32_e32 v130, vcc, 0x22000, v128
	s_nop 1
	v_addc_co_u32_e32 v131, vcc, 0, v129, vcc
	s_nop 1
	v_mov_b32_dpp v131, v133 quad_perm:[1,0,3,2] row_mask:0xf bank_mask:0xf
	v_perm_b32 v142, v131, v133, v250
	s_waitcnt lgkmcnt(0)
	s_nop 1
	v_mov_b32_dpp v131, v132 quad_perm:[1,0,3,2] row_mask:0xf bank_mask:0xf
	v_add_co_u32_e32 v136, vcc, 0x44000, v128
	s_nop 1
	v_addc_co_u32_e32 v137, vcc, 0, v129, vcc
	v_perm_b32 v143, v131, v132, v250
	v_add_co_u32_e32 v128, vcc, 0x66000, v128
	s_nop 1
	v_addc_co_u32_e32 v129, vcc, 0, v129, vcc
	v_cndmask_b32_e64 v144, v141, v140, s[98:99]
	v_cndmask_b32_e64 v145, v143, v142, s[98:99]
	s_nop 0
	v_mov_b32_dpp v146, v144 quad_perm:[2,3,0,1] row_mask:0xf bank_mask:0xf
	v_mov_b32_dpp v147, v145 quad_perm:[2,3,0,1] row_mask:0xf bank_mask:0xf
	v_cndmask_b32_e64 v152, v140, v146, s[98:99]
	v_cndmask_b32_e64 v153, v146, v141, s[98:99]
	v_lshl_add_u64 v[158:159], v[156:157], 0, v[150:151]
	v_cndmask_b32_e64 v154, v142, v147, s[98:99]
	v_cndmask_b32_e64 v155, v147, v143, s[98:99]
	global_store_dwordx2 v[156:157], v[152:153], off offset:352
	global_store_dwordx2 v[158:159], v[154:155], off offset:352
